# one static s_setprio 1 at entry for workgroups >= 256 (the second workgroup of each CU), nothing else changed
# baseline (speedup 1.0000x reference)
; DI unsigned xb_add(unsigned* p, unsigned v) { return __hip_atomic_fetch_add(p, v, __ATOMIC_RELAXED, __HIP_MEMORY_SCOPE_AGENT); }
; DI unsigned xb_xcc_id() { return (unsigned)__builtin_amdgcn_s_getreg((3 << 11) | 20) & 0xFu; }
; DI XcdBarrier xcd_barrier_post(unsigned* bar) {
;   XcdBarrier b; b.bar = bar; b.x = xb_xcc_id(); b.nloc = 0u; b.nx = 0u;
;   if (threadIdx.x == 0) (void)xb_add(&bar[XB_XCNT(b.x)], 1u);
;   return b;
; }
; __global__ void __launch_bounds__(256, 2) mega_kernel(Params P, int ph_begin, int ph_end) {
;   __shared__ __attribute__((aligned(1024))) char smem[65536];
;   cg::grid_group grid = cg::this_grid();
;   XcdBarrier xb = xcd_barrier_post((unsigned*)(P.ws + OFF_BAR));
_Z11mega_kernel6Paramsii:
	s_load_dwordx2 s[74:75], s[0:1], 0xb0
	s_mov_b32 s68, s2
	s_cmp_ge_u32 s2, 0x100
	s_cbranch_scc0 .Lprio_done
	s_setprio 1
.Lprio_done:
	s_add_u32 s2, s0, 0xc0
	s_addc_u32 s3, s1, 0
	s_load_dword s8, s[0:1], 0xc8
	s_load_dwordx2 s[70:71], s[0:1], 0xc0
	v_writelane_b32 v252, s2, 0
	s_waitcnt lgkmcnt(0)
	s_add_u32 s4, s74, 0x1f400000
	s_addc_u32 s5, s75, 0
	v_writelane_b32 v252, s3, 1
	s_getreg_b32 s2, hwreg(HW_REG_XCC_ID, 0, 4)
	v_writelane_b32 v252, s2, 2
	s_and_b32 s2, s2, 15
	v_writelane_b32 v252, s2, 3
	v_and_b32_e32 v161, 0x3ff, v0
	v_cmp_eq_u32_e64 s[6:7], 0, v161
	s_mov_b64 s[2:3], exec
	s_nop 0
	v_writelane_b32 v252, s6, 4
	s_nop 1
	v_writelane_b32 v252, s7, 5
	s_and_b64 s[6:7], s[2:3], s[6:7]
	s_mov_b64 exec, s[6:7]
	s_cbranch_execz .LBB0_3
	s_mov_b64 s[6:7], exec
	v_mbcnt_lo_u32_b32 v1, s6, 0
	v_mbcnt_hi_u32_b32 v1, s7, v1
	v_cmp_eq_u32_e32 vcc, 0, v1
	s_and_b64 s[10:11], exec, vcc
	s_mov_b64 exec, s[10:11]
	s_cbranch_execz .LBB0_3
	v_readlane_b32 s9, v252, 3
	s_lshl_b32 s9, s9, 8
	s_bcnt1_i32_b64 s6, s[6:7]
	v_mov_b32_e32 v1, s9
	v_mov_b32_e32 v2, s6
	global_atomic_add v1, v2, s[4:5] offset:1024
